# MLA item epilogue: adjacent 8-byte groups exchanged across half-waves (v_permlane32_swap) -> four 16-byte stores per lane instead of eight 8-byte stores
# baseline (speedup 1.0000x reference)
; template <int MODE>
; DI void attn_item(const Params& p, int layer, int bh, int qb, char* lds) {
;     ...
;         for (int sub = 0; sub < 2; ++sub) {
; #pragma unroll
;           for (int st = 0; st < QS; ++st) {
;             bf16x8 kf = *(const bf16x8*)(Ks + (32 * sub + l32) * KSTR + ((mp * QS + st) * 16 + hh * 8) * 2);
;             if (st == 0) s[sub] = MFMA(kf, qf[mp][st], c0tile); else s[sub] = MFMA(kf, qf[mp][st], s[sub]);
;           }
;         }
;         __builtin_amdgcn_iglp_opt(1);
;         __builtin_amdgcn_s_setprio(0);
;         if (NMAP == 1) {
;           lds_s16x4* vb = (lds_s16x4*)(Ks + KBYTES + vlane);
; #pragma unroll
;           for (int i = 0; i < 16; ++i) {
;             const int sub_ = i >> 3, ks_ = (i >> 2) & 1, dt_ = (i >> 1) & 1, g_ = i & 1;
;             vpre[i] = __builtin_amdgcn_ds_read_tr16_b64_v4i16(vb + ((32 * sub_ + 16 * ks_ + 8 * g_) * VSTR + 64 * dt_) / 8);
;           }
;           __builtin_amdgcn_sched_barrier(0);
;         }
;         if (MODE != 0 && !far) {
; #pragma unroll
;           for (int sub = 0; sub < 2; ++sub)
; #pragma unroll
;             for (int r = 0; r < 16; ++r) s[sub][r] += brow[32 * sub + (r & 3) + 8 * (r >> 2)];
;         }
;         const bool first = (MODE != 2) && (t == 0) && (mp == 0);
;         auto rebase = [&]() {
;           float mx = fmaxf(fmaxf(s[0][0], s[0][1]), s[0][2]);
; #pragma unroll
;           for (int r = 3; r < 15; r += 2) mx = fmaxf(fmaxf(mx, s[0][r]), s[0][r + 1]);
;           mx = fmaxf(mx, s[0][15]);
; #pragma unroll
;           for (int r = 0; r < 16; r += 2) mx = fmaxf(fmaxf(mx, s[1][r]), s[1][r + 1]);
;           const float rm = xchg_max(mx);
;           float delta = first ? rm : fmaxf(rm, 0.f);
;           if (delta < -1e29f) delta = 0.f;
;           m += delta;
;           const float alpha = __builtin_amdgcn_exp2f(-delta);
; #pragma unroll
;           for (int mq = 0; mq < NMAP; ++mq) {
;             l[mq] *= alpha;
; #pragma unroll
;             for (int r = 0; r < 16; ++r) { O[mq][0][r] *= alpha; O[mq][1][r] *= alpha; }
;           }
; #pragma unroll
;           for (int r = 0; r < 16; ++r) { s[0][r] -= delta; s[1][r] -= delta; }
;           set_c0(cb - m);
;         };
;         float ps;
;         auto smpass = [&]() {
;           ps = 0.f;
; #pragma unroll
;           for (int sub = 0; sub < 2; ++sub)
; #pragma unroll
;             for (int ks = 0; ks < 2; ++ks)
.Lmla_loop:
	ds_read_b128 v[176:179], v200 offset:27648
	ds_read_b128 v[180:183], v200 offset:27680
	ds_read_b128 v[222:225], v200 offset:27712
	s_waitcnt vmcnt(3)
	ds_write_b128 v202, v[96:99] offset:2048
	ds_write_b64 v203, v[100:101] offset:2048
	ds_write_b128 v207, v[188:191] offset:40960
	buffer_load_dwordx4 v[96:99], v187, s[20:23], s62 offen
	buffer_load_dwordx2 v[100:101], v205, s[20:23], s62 offen
	buffer_load_dwordx4 v[188:191], v187, s[12:15], s29 offen
	s_add_u32 s62, s62, 0x3000
	s_add_u32 s29, s29, 0x2000
	v_exp_f32_e32 v0, v64
	v_exp_f32_e32 v1, v65
	v_exp_f32_e32 v2, v66
	v_exp_f32_e32 v3, v67
	v_add_f32_e32 v10, v0, v1
	v_cvt_pk_bf16_f32 v160, v0, v1
	s_waitcnt lgkmcnt(5)
	v_mfma_f32_32x32x16_bf16 v[128:143], v[176:179], v[104:107], v[48:63]
	ds_read_b128 v[226:229], v200 offset:27744
	s_waitcnt lgkmcnt(5)
	v_mfma_f32_32x32x16_bf16 v[128:143], v[180:183], v[108:111], v[128:143]
	ds_read_b64_tr_b16 v[176:177], v201 offset:15360
	ds_read_b64_tr_b16 v[178:179], v201 offset:16896
	v_add_f32_e32 v10, v10, v2
	v_add_f32_e32 v10, v10, v3
	v_cvt_pk_bf16_f32 v161, v2, v3
	s_waitcnt lgkmcnt(6)
	v_mfma_f32_32x32x16_bf16 v[128:143], v[222:225], v[112:115], v[128:143]
	ds_read_b64_tr_b16 v[180:181], v201 offset:15424
	ds_read_b64_tr_b16 v[182:183], v201 offset:16960
	v_exp_f32_e32 v6, v68
	v_exp_f32_e32 v7, v69
	v_exp_f32_e32 v8, v70
	v_exp_f32_e32 v9, v71
	v_add_f32_e32 v10, v10, v6
	s_waitcnt lgkmcnt(4)
	v_mfma_f32_32x32x16_bf16 v[128:143], v[226:229], v[116:119], v[128:143]
	ds_read_b128 v[222:225], v200 offset:27776
	v_add_f32_e32 v10, v10, v7
	v_cvt_pk_bf16_f32 v162, v6, v7
	v_add_f32_e32 v10, v10, v8
	v_add_f32_e32 v10, v10, v9
	v_cvt_pk_bf16_f32 v163, v8, v9
	s_waitcnt lgkmcnt(3)
	s_nop 0
	v_mfma_f32_32x32x16_bf16 v[32:47], v[176:179], v[160:163], v[32:47]
	ds_read_b128 v[226:229], v200 offset:27808
	v_exp_f32_e32 v0, v72
	v_exp_f32_e32 v1, v73
	v_exp_f32_e32 v2, v74
	s_waitcnt lgkmcnt(2)
	v_mfma_f32_32x32x16_bf16 v[16:31], v[180:183], v[160:163], v[16:31]
	ds_read_b128 v[176:179], v200 offset:34304
	v_exp_f32_e32 v3, v75
	v_add_f32_e32 v11, v0, v1
	v_cvt_pk_bf16_f32 v164, v0, v1
	v_add_f32_e32 v11, v11, v2
	s_waitcnt lgkmcnt(2)
	v_mfma_f32_32x32x16_bf16 v[128:143], v[222:225], v[120:123], v[128:143]
	ds_read_b64_tr_b16 v[180:181], v201 offset:18432
	ds_read_b64_tr_b16 v[182:183], v201 offset:19968
	v_add_f32_e32 v11, v11, v3
	v_cvt_pk_bf16_f32 v165, v2, v3
	v_exp_f32_e32 v6, v76
	v_exp_f32_e32 v7, v77
	s_waitcnt lgkmcnt(3)
	v_mfma_f32_32x32x16_bf16 v[128:143], v[226:229], v[124:127], v[128:143]
	ds_read_b64_tr_b16 v[222:223], v201 offset:18496
	ds_read_b64_tr_b16 v[224:225], v201 offset:20032
	v_exp_f32_e32 v8, v78
	v_exp_f32_e32 v9, v79
	v_add_f32_e32 v11, v11, v6
	v_add_f32_e32 v11, v11, v7
	s_waitcnt lgkmcnt(4)
	v_mfma_f32_32x32x16_bf16 v[144:159], v[176:179], v[104:107], v[48:63]
	ds_read_b128 v[226:229], v200 offset:34336
	v_cvt_pk_bf16_f32 v166, v6, v7
	v_add_f32_e32 v11, v11, v8
	v_add_f32_e32 v11, v11, v9
	v_cvt_pk_bf16_f32 v167, v8, v9
	s_waitcnt lgkmcnt(3)
	s_nop 0
	v_mfma_f32_32x32x16_bf16 v[32:47], v[180:183], v[164:167], v[32:47]
	ds_read_b128 v[176:179], v200 offset:34368
	v_exp_f32_e32 v0, v80
	v_exp_f32_e32 v1, v81
	v_exp_f32_e32 v2, v82
	s_waitcnt lgkmcnt(2)
	v_mfma_f32_32x32x16_bf16 v[16:31], v[222:225], v[164:167], v[16:31]
	ds_read_b128 v[180:183], v200 offset:34400
	v_exp_f32_e32 v3, v83
	v_add_f32_e32 v12, v0, v1
	v_cvt_pk_bf16_f32 v168, v0, v1
	v_add_f32_e32 v12, v12, v2
	s_waitcnt lgkmcnt(2)
	v_mfma_f32_32x32x16_bf16 v[144:159], v[226:229], v[108:111], v[144:159]
	ds_read_b64_tr_b16 v[222:223], v201 offset:21504
	ds_read_b64_tr_b16 v[224:225], v201 offset:23040
	v_add_f32_e32 v12, v12, v3
	v_cvt_pk_bf16_f32 v169, v2, v3
	v_exp_f32_e32 v6, v84
	v_exp_f32_e32 v7, v85
	s_waitcnt lgkmcnt(3)
	v_mfma_f32_32x32x16_bf16 v[144:159], v[176:179], v[112:115], v[144:159]
	ds_read_b64_tr_b16 v[226:227], v201 offset:21568
	ds_read_b64_tr_b16 v[228:229], v201 offset:23104
	v_exp_f32_e32 v8, v86
	v_exp_f32_e32 v9, v87
	v_add_f32_e32 v12, v12, v6
	v_add_f32_e32 v12, v12, v7
	s_waitcnt lgkmcnt(4)
	v_mfma_f32_32x32x16_bf16 v[144:159], v[180:183], v[116:119], v[144:159]
	ds_read_b128 v[176:179], v200 offset:34432
	v_cvt_pk_bf16_f32 v170, v6, v7
	v_add_f32_e32 v12, v12, v8
	v_add_f32_e32 v12, v12, v9
	v_cvt_pk_bf16_f32 v171, v8, v9
	s_waitcnt lgkmcnt(3)
	s_nop 0
	v_mfma_f32_32x32x16_bf16 v[32:47], v[222:225], v[168:171], v[32:47]
	ds_read_b128 v[180:183], v200 offset:34464
	v_exp_f32_e32 v0, v88
	v_exp_f32_e32 v1, v89
	v_exp_f32_e32 v2, v90
	v_exp_f32_e32 v3, v91
	s_waitcnt lgkmcnt(2)
	v_mfma_f32_32x32x16_bf16 v[16:31], v[226:229], v[168:171], v[16:31]
	ds_read_b64_tr_b16 v[222:223], v201 offset:24576
	ds_read_b64_tr_b16 v[224:225], v201 offset:26112
	v_add_f32_e32 v13, v0, v1
	v_cvt_pk_bf16_f32 v172, v0, v1
	v_add_f32_e32 v13, v13, v2
	v_add_f32_e32 v13, v13, v3
	v_cvt_pk_bf16_f32 v173, v2, v3
	s_waitcnt lgkmcnt(3)
	v_mfma_f32_32x32x16_bf16 v[144:159], v[176:179], v[120:123], v[144:159]
	ds_read_b64_tr_b16 v[226:227], v201 offset:24640
	ds_read_b64_tr_b16 v[228:229], v201 offset:26176
	v_exp_f32_e32 v6, v92
	v_exp_f32_e32 v7, v93
	v_exp_f32_e32 v8, v94
	v_exp_f32_e32 v9, v95
	v_add_f32_e32 v13, v13, v6
	s_waitcnt lgkmcnt(4)
	v_mfma_f32_32x32x16_bf16 v[144:159], v[180:183], v[124:127], v[144:159]
	v_add_f32_e32 v13, v13, v7
	v_cvt_pk_bf16_f32 v174, v6, v7
	v_add_f32_e32 v13, v13, v8
	v_add_f32_e32 v13, v13, v9
	v_cvt_pk_bf16_f32 v175, v8, v9
	s_waitcnt lgkmcnt(2)
	s_nop 0
	v_mfma_f32_32x32x16_bf16 v[32:47], v[222:225], v[172:175], v[32:47]
	s_waitcnt lgkmcnt(0)
	v_mfma_f32_32x32x16_bf16 v[16:31], v[226:229], v[172:175], v[16:31]
	v_add_f32_e32 v10, v10, v11
	v_add_f32_e32 v12, v12, v13
	v_add_f32_e32 v10, v10, v12
	v_add_f32_e32 v192, v192, v10
	v_max_f32_e32 v193, v193, v10
	s_waitcnt lgkmcnt(0)
	s_barrier
; template <int MODE>
; DI void attn_item(const Params& p, int layer, int bh, int qb, char* lds) {
;     ...
;         for (int sub = 0; sub < 2; ++sub) {
; #pragma unroll
;           for (int st = 0; st < QS; ++st) {
;             bf16x8 kf = *(const bf16x8*)(Ks + (32 * sub + l32) * KSTR + ((mp * QS + st) * 16 + hh * 8) * 2);
;             if (st == 0) s[sub] = MFMA(kf, qf[mp][st], c0tile); else s[sub] = MFMA(kf, qf[mp][st], s[sub]);
;           }
;         }
;         __builtin_amdgcn_iglp_opt(1);
;         __builtin_amdgcn_s_setprio(0);
;         if (NMAP == 1) {
;           lds_s16x4* vb = (lds_s16x4*)(Ks + KBYTES + vlane);
; #pragma unroll
;           for (int i = 0; i < 16; ++i) {
;             const int sub_ = i >> 3, ks_ = (i >> 2) & 1, dt_ = (i >> 1) & 1, g_ = i & 1;
;             vpre[i] = __builtin_amdgcn_ds_read_tr16_b64_v4i16(vb + ((32 * sub_ + 16 * ks_ + 8 * g_) * VSTR + 64 * dt_) / 8);
;           }
;           __builtin_amdgcn_sched_barrier(0);
;         }
;         if (MODE != 0 && !far) {
; #pragma unroll
;           for (int sub = 0; sub < 2; ++sub)
; #pragma unroll
;             for (int r = 0; r < 16; ++r) s[sub][r] += brow[32 * sub + (r & 3) + 8 * (r >> 2)];
;         }
;         const bool first = (MODE != 2) && (t == 0) && (mp == 0);
;         auto rebase = [&]() {
;           float mx = fmaxf(fmaxf(s[0][0], s[0][1]), s[0][2]);
; #pragma unroll
;           for (int r = 3; r < 15; r += 2) mx = fmaxf(fmaxf(mx, s[0][r]), s[0][r + 1]);
;           mx = fmaxf(mx, s[0][15]);
; #pragma unroll
;           for (int r = 0; r < 16; r += 2) mx = fmaxf(fmaxf(mx, s[1][r]), s[1][r + 1]);
;           const float rm = xchg_max(mx);
;           float delta = first ? rm : fmaxf(rm, 0.f);
;           if (delta < -1e29f) delta = 0.f;
;           m += delta;
;           const float alpha = __builtin_amdgcn_exp2f(-delta);
; #pragma unroll
;           for (int mq = 0; mq < NMAP; ++mq) {
;             l[mq] *= alpha;
; #pragma unroll
;             for (int r = 0; r < 16; ++r) { O[mq][0][r] *= alpha; O[mq][1][r] *= alpha; }
;           }
; #pragma unroll
;           for (int r = 0; r < 16; ++r) { s[0][r] -= delta; s[1][r] -= delta; }
;           set_c0(cb - m);
;         };
;         float ps;
;         auto smpass = [&]() {
;           ps = 0.f;
; #pragma unroll
;           for (int sub = 0; sub < 2; ++sub)
; #pragma unroll
;             for (int ks = 0; ks < 2; ++ks)
	ds_read_b128 v[176:179], v200 offset:2048
	ds_read_b128 v[180:183], v200 offset:2080
	ds_read_b128 v[222:225], v200 offset:2112
	s_waitcnt vmcnt(3)
	ds_write_b128 v202, v[230:233] offset:27648
	ds_write_b64 v203, v[234:235] offset:27648
	ds_write_b128 v207, v[236:239] offset:15360
	buffer_load_dwordx4 v[230:233], v187, s[20:23], s62 offen
	buffer_load_dwordx2 v[234:235], v205, s[20:23], s62 offen
	buffer_load_dwordx4 v[236:239], v187, s[12:15], s29 offen
	s_add_u32 s62, s62, 0x3000
	s_add_u32 s29, s29, 0x2000
	v_exp_f32_e32 v0, v128
	v_exp_f32_e32 v1, v129
	v_exp_f32_e32 v2, v130
	v_exp_f32_e32 v3, v131
	v_add_f32_e32 v10, v0, v1
	v_cvt_pk_bf16_f32 v160, v0, v1
	s_waitcnt lgkmcnt(5)
	v_mfma_f32_32x32x16_bf16 v[64:79], v[176:179], v[104:107], v[48:63]
	ds_read_b128 v[226:229], v200 offset:2144
	s_waitcnt lgkmcnt(5)
	v_mfma_f32_32x32x16_bf16 v[64:79], v[180:183], v[108:111], v[64:79]
	ds_read_b64_tr_b16 v[176:177], v201 offset:40960
	ds_read_b64_tr_b16 v[178:179], v201 offset:42496
	v_add_f32_e32 v10, v10, v2
	v_add_f32_e32 v10, v10, v3
	v_cvt_pk_bf16_f32 v161, v2, v3
	s_waitcnt lgkmcnt(6)
	v_mfma_f32_32x32x16_bf16 v[64:79], v[222:225], v[112:115], v[64:79]
	ds_read_b64_tr_b16 v[180:181], v201 offset:41024
	ds_read_b64_tr_b16 v[182:183], v201 offset:42560
	v_exp_f32_e32 v6, v132
	v_exp_f32_e32 v7, v133
	v_exp_f32_e32 v8, v134
	v_exp_f32_e32 v9, v135
	v_add_f32_e32 v10, v10, v6
	s_waitcnt lgkmcnt(4)
	v_mfma_f32_32x32x16_bf16 v[64:79], v[226:229], v[116:119], v[64:79]
	ds_read_b128 v[222:225], v200 offset:2176
	v_add_f32_e32 v10, v10, v7
	v_cvt_pk_bf16_f32 v162, v6, v7
	v_add_f32_e32 v10, v10, v8
	v_add_f32_e32 v10, v10, v9
	v_cvt_pk_bf16_f32 v163, v8, v9
	s_waitcnt lgkmcnt(3)
	s_nop 0
	v_mfma_f32_32x32x16_bf16 v[32:47], v[176:179], v[160:163], v[32:47]
	ds_read_b128 v[226:229], v200 offset:2208
	v_exp_f32_e32 v0, v136
	v_exp_f32_e32 v1, v137
	v_exp_f32_e32 v2, v138
	s_waitcnt lgkmcnt(2)
	v_mfma_f32_32x32x16_bf16 v[16:31], v[180:183], v[160:163], v[16:31]
	ds_read_b128 v[176:179], v200 offset:8704
	v_exp_f32_e32 v3, v139
	v_add_f32_e32 v11, v0, v1
	v_cvt_pk_bf16_f32 v164, v0, v1
	v_add_f32_e32 v11, v11, v2
	s_waitcnt lgkmcnt(2)
	v_mfma_f32_32x32x16_bf16 v[64:79], v[222:225], v[120:123], v[64:79]
	ds_read_b64_tr_b16 v[180:181], v201 offset:44032
	ds_read_b64_tr_b16 v[182:183], v201 offset:45568
	v_add_f32_e32 v11, v11, v3
	v_cvt_pk_bf16_f32 v165, v2, v3
	v_exp_f32_e32 v6, v140
	v_exp_f32_e32 v7, v141
	s_waitcnt lgkmcnt(3)
	v_mfma_f32_32x32x16_bf16 v[64:79], v[226:229], v[124:127], v[64:79]
	ds_read_b64_tr_b16 v[222:223], v201 offset:44096
	ds_read_b64_tr_b16 v[224:225], v201 offset:45632
	v_exp_f32_e32 v8, v142
	v_exp_f32_e32 v9, v143
	v_add_f32_e32 v11, v11, v6
	v_add_f32_e32 v11, v11, v7
	s_waitcnt lgkmcnt(4)
	v_mfma_f32_32x32x16_bf16 v[80:95], v[176:179], v[104:107], v[48:63]
	ds_read_b128 v[226:229], v200 offset:8736
	v_cvt_pk_bf16_f32 v166, v6, v7
	v_add_f32_e32 v11, v11, v8
	v_add_f32_e32 v11, v11, v9
	v_cvt_pk_bf16_f32 v167, v8, v9
	s_waitcnt lgkmcnt(3)
	s_nop 0
	v_mfma_f32_32x32x16_bf16 v[32:47], v[180:183], v[164:167], v[32:47]
	ds_read_b128 v[176:179], v200 offset:8768
	v_exp_f32_e32 v0, v144
	v_exp_f32_e32 v1, v145
	v_exp_f32_e32 v2, v146
	s_waitcnt lgkmcnt(2)
	v_mfma_f32_32x32x16_bf16 v[16:31], v[222:225], v[164:167], v[16:31]
	ds_read_b128 v[180:183], v200 offset:8800
	v_exp_f32_e32 v3, v147
	v_add_f32_e32 v12, v0, v1
	v_cvt_pk_bf16_f32 v168, v0, v1
	v_add_f32_e32 v12, v12, v2
	s_waitcnt lgkmcnt(2)
	v_mfma_f32_32x32x16_bf16 v[80:95], v[226:229], v[108:111], v[80:95]
	ds_read_b64_tr_b16 v[222:223], v201 offset:47104
	ds_read_b64_tr_b16 v[224:225], v201 offset:48640
	v_add_f32_e32 v12, v12, v3
	v_cvt_pk_bf16_f32 v169, v2, v3
	v_exp_f32_e32 v6, v148
	v_exp_f32_e32 v7, v149
	s_waitcnt lgkmcnt(3)
	v_mfma_f32_32x32x16_bf16 v[80:95], v[176:179], v[112:115], v[80:95]
	ds_read_b64_tr_b16 v[226:227], v201 offset:47168
	ds_read_b64_tr_b16 v[228:229], v201 offset:48704
	v_exp_f32_e32 v8, v150
	v_exp_f32_e32 v9, v151
	v_add_f32_e32 v12, v12, v6
	v_add_f32_e32 v12, v12, v7
	s_waitcnt lgkmcnt(4)
	v_mfma_f32_32x32x16_bf16 v[80:95], v[180:183], v[116:119], v[80:95]
	ds_read_b128 v[176:179], v200 offset:8832
	v_cvt_pk_bf16_f32 v170, v6, v7
	v_add_f32_e32 v12, v12, v8
	v_add_f32_e32 v12, v12, v9
	v_cvt_pk_bf16_f32 v171, v8, v9
	s_waitcnt lgkmcnt(3)
	s_nop 0
	v_mfma_f32_32x32x16_bf16 v[32:47], v[222:225], v[168:171], v[32:47]
	ds_read_b128 v[180:183], v200 offset:8864
	v_exp_f32_e32 v0, v152
	v_exp_f32_e32 v1, v153
	v_exp_f32_e32 v2, v154
	v_exp_f32_e32 v3, v155
	s_waitcnt lgkmcnt(2)
	v_mfma_f32_32x32x16_bf16 v[16:31], v[226:229], v[168:171], v[16:31]
	ds_read_b64_tr_b16 v[222:223], v201 offset:50176
	ds_read_b64_tr_b16 v[224:225], v201 offset:51712
	v_add_f32_e32 v13, v0, v1
	v_cvt_pk_bf16_f32 v172, v0, v1
	v_add_f32_e32 v13, v13, v2
	v_add_f32_e32 v13, v13, v3
	v_cvt_pk_bf16_f32 v173, v2, v3
	s_waitcnt lgkmcnt(3)
	v_mfma_f32_32x32x16_bf16 v[80:95], v[176:179], v[120:123], v[80:95]
	ds_read_b64_tr_b16 v[226:227], v201 offset:50240
	ds_read_b64_tr_b16 v[228:229], v201 offset:51776
	v_exp_f32_e32 v6, v156
	v_exp_f32_e32 v7, v157
	v_exp_f32_e32 v8, v158
	v_exp_f32_e32 v9, v159
	v_add_f32_e32 v13, v13, v6
	s_waitcnt lgkmcnt(4)
	v_mfma_f32_32x32x16_bf16 v[80:95], v[180:183], v[124:127], v[80:95]
	v_add_f32_e32 v13, v13, v7
	v_cvt_pk_bf16_f32 v174, v6, v7
	v_add_f32_e32 v13, v13, v8
	v_add_f32_e32 v13, v13, v9
	v_cvt_pk_bf16_f32 v175, v8, v9
	s_waitcnt lgkmcnt(2)
	s_nop 0
	v_mfma_f32_32x32x16_bf16 v[32:47], v[222:225], v[172:175], v[32:47]
	s_waitcnt lgkmcnt(0)
	v_mfma_f32_32x32x16_bf16 v[16:31], v[226:229], v[172:175], v[16:31]
	v_add_f32_e32 v10, v10, v11
	v_add_f32_e32 v12, v12, v13
	v_add_f32_e32 v10, v10, v12
	v_add_f32_e32 v192, v192, v10
	v_max_f32_e32 v193, v193, v10
	s_add_u32 s28, s28, 2
	s_cmpk_lt_u32 s28, 0x80
	s_waitcnt lgkmcnt(0)
	s_barrier
; DI unsigned pk2(float lo, float hi) { f32x2 v = {lo, hi}; b16x2 r = __builtin_convertvector(v, b16x2); return __builtin_bit_cast(unsigned, r); }
; DI float bflo(unsigned w) { return __uint_as_float(w << 16); }
; DI float bfhi(unsigned w) { return __uint_as_float(w & 0xffff0000u); }
; template <int MODE>
; DI void attn_item(const Params& p, int layer, int bh, int qb, char* lds) {
;     ...
;   __syncthreads();
;   const size_t trow = (size_t)b * S + q0w + l32;
;   const u16* grow = (const u16*)(p.ws + OFF_H) + trow * DIN + C_GATE + ocol;
;   u16* orow = (u16*)(p.ws + OFF_OB) + trow * DM + ocol;
;   float inv0 = 1.f / xchg_sum(l[0]);
;   if (MODE == 1) {
;     const float* lm = (const float*)(p.ws + OFF_LAM);
;     const float lam = lm[layer], post = lm[4 + layer];
;     const float inv1 = lam / xchg_sum(l[1]);
;     float ss = 0.f;
; #pragma unroll
;     for (int dt = 0; dt < 2; ++dt)
; #pragma unroll
;       for (int r = 0; r < 16; ++r) { float v = O[0][dt][r] * inv0 - O[NMAP - 1][dt][r] * inv1; O[0][dt][r] = v; ss += v * v; }
;     ss = xchg_sum(ss);
;     inv0 = rsqrtf(ss * (1.f / 64.f) + 1e-6f) * post;
;   }
; #pragma unroll
;   for (int dt = 0; dt < 2; ++dt)
; #pragma unroll
;     for (int g = 0; g < 4; ++g) {
;       const int d = 32 * dt + 8 * g + 4 * hh;
;       u32x2 gw = *(const u32x2*)(grow + d);
;       float v0 = O[0][dt][4 * g + 0] * inv0, v1 = O[0][dt][4 * g + 1] * inv0, v2 = O[0][dt][4 * g + 2] * inv0, v3 = O[0][dt][4 * g + 3] * inv0;
;       if (MODE == 1) { const float* sl = p.subln + layer * 64 + d; v0 *= sl[0]; v1 *= sl[1]; v2 *= sl[2]; v3 *= sl[3]; }
;       v0 *= bflo(gw[0]); v1 *= bfhi(gw[0]); v2 *= bflo(gw[1]); v3 *= bfhi(gw[1]);
;       u32x2 ow = {pk2(v0, v1), pk2(v2, v3)};
;     ...
;       if (MODE == PROBE_ZERO_MODE) { ow[0] = 0u; ow[1] = 0u; }
;     ...
;       *(u32x2*)(orow + d) = ow;
;     }
	s_cbranch_scc1 .Lmla_loop
	s_waitcnt vmcnt(0)
	s_lshl_b64 s[6:7], s[10:11], 13
	v_ashrrev_i32_e32 v187, 31, v186
	v_lshl_add_u64 v[0:1], s[6:7], 0, v[186:187]
	v_or_b32_e32 v0, v0, v204
	v_mov_b32_e32 v2, s34
	v_mov_b32_e32 v3, s35
	v_mad_u64_u32 v[2:3], s[6:7], v0, s64, v[2:3]
	v_mad_i32_i24 v3, v1, s64, v3
	s_lshl_b32 s4, s52, 7
	v_lshl_add_u32 v12, v206, 1, s4
	v_mov_b32_e32 v13, 0
	v_lshl_add_u64 v[6:7], v[2:3], 0, v[12:13]
	s_mov_b64 s[6:7], 0x6058ec0
	v_lshl_add_u64 v[6:7], v[6:7], 0, s[6:7]
	global_load_dwordx2 v[64:65], v[6:7], off offset:0
	global_load_dwordx2 v[66:67], v[6:7], off offset:16
	global_load_dwordx2 v[68:69], v[6:7], off offset:32
	global_load_dwordx2 v[70:71], v[6:7], off offset:48
	global_load_dwordx2 v[72:73], v[6:7], off offset:64
	global_load_dwordx2 v[74:75], v[6:7], off offset:80
	global_load_dwordx2 v[76:77], v[6:7], off offset:96
	global_load_dwordx2 v[78:79], v[6:7], off offset:112
	v_readlane_b32 s6, v254, 49
	v_readlane_b32 s7, v254, 50
	v_lshlrev_b64 v[0:1], 11, v[0:1]
	s_nop 0
	v_lshl_add_u64 v[0:1], s[6:7], 0, v[0:1]
	v_lshl_add_u32 v14, v206, 2, s4
	v_mov_b32_e32 v15, 0
	v_lshl_add_u64 v[8:9], v[0:1], 0, v[14:15]
	v_cmp_nge_f32_e32 vcc, s94, v193
	s_nop 0
	s_cmp_lg_u64 vcc, 0
	s_cselect_b32 s24, 1, 0
	v_mov_b32_e32 v196, s24
	v_lshrrev_b32_e32 v197, 6, v184
	v_lshlrev_b32_e32 v197, 2, v197
	ds_write_b32 v197, v196 offset:0
	s_waitcnt lgkmcnt(0)
	s_barrier
	v_mov_b32_e32 v197, 0
	ds_read_b128 v[176:179], v197 offset:0
	ds_read_b128 v[180:183], v197 offset:16
	v_mov_b32_e32 v2, v192
	s_nop 1
	v_permlane32_swap_b32_e32 v192, v2
	v_add_f32_e32 v2, v192, v2
	v_div_scale_f32 v3, s[4:5], v2, v2, 1.0
	v_rcp_f32_e32 v4, v3
	s_nop 0
	v_fma_f32 v10, -v3, v4, 1.0
	v_fmac_f32_e32 v4, v10, v4
	v_div_scale_f32 v10, vcc, 1.0, v2, 1.0
	v_mul_f32_e32 v11, v10, v4
	v_fma_f32 v12, -v3, v11, v10
	v_fmac_f32_e32 v11, v12, v4
	v_fma_f32 v3, -v3, v11, v10
	s_nop 1
	v_div_fmas_f32 v3, v3, v4, v11
	v_div_fixup_f32 v2, v3, v2, 1.0
	s_waitcnt lgkmcnt(0)
	v_or3_b32 v196, v176, v177, v178
	v_or3_b32 v196, v196, v179, v180
	v_or3_b32 v196, v196, v181, v182
	v_or_b32_e32 v196, v196, v183
	s_nop 0
	v_readfirstlane_b32 s24, v196
	s_barrier
	s_cmp_lg_u32 s24, 0
	s_cbranch_scc1 .Lmla_slow
	s_waitcnt vmcnt(0)
	v_mul_f32_e32 v32, v32, v2
	v_mul_f32_e32 v33, v33, v2
	v_mul_f32_e32 v34, v34, v2
	v_mul_f32_e32 v35, v35, v2
	v_lshlrev_b32_e32 v196, 16, v64
	v_and_b32_e32 v197, 0xffff0000, v64
	v_mul_f32_e32 v32, v32, v196
	v_mul_f32_e32 v33, v33, v197
	v_lshlrev_b32_e32 v196, 16, v65
	v_and_b32_e32 v197, 0xffff0000, v65
	v_mul_f32_e32 v34, v34, v196
	v_mul_f32_e32 v35, v35, v197
	v_cvt_pk_bf16_f32 v32, v32, v33
	v_cvt_pk_bf16_f32 v33, v34, v35
	v_mul_f32_e32 v36, v36, v2
	v_mul_f32_e32 v37, v37, v2
	v_mul_f32_e32 v38, v38, v2
	v_mul_f32_e32 v39, v39, v2
	v_lshlrev_b32_e32 v196, 16, v66
	v_and_b32_e32 v197, 0xffff0000, v66
	v_mul_f32_e32 v36, v36, v196
	v_mul_f32_e32 v37, v37, v197
	v_lshlrev_b32_e32 v196, 16, v67
	v_and_b32_e32 v197, 0xffff0000, v67
	v_mul_f32_e32 v38, v38, v196
	v_mul_f32_e32 v39, v39, v197
	v_cvt_pk_bf16_f32 v34, v36, v37
	v_cvt_pk_bf16_f32 v35, v38, v39
	s_nop 0
	v_permlane32_swap_b32_e32 v32, v34
	v_permlane32_swap_b32_e32 v33, v35
	global_store_dwordx4 v[8:9], v[32:35], off offset:0
	v_mul_f32_e32 v40, v40, v2
	v_mul_f32_e32 v41, v41, v2
	v_mul_f32_e32 v42, v42, v2
	v_mul_f32_e32 v43, v43, v2
	v_lshlrev_b32_e32 v196, 16, v68
	v_and_b32_e32 v197, 0xffff0000, v68
	v_mul_f32_e32 v40, v40, v196
	v_mul_f32_e32 v41, v41, v197
	v_lshlrev_b32_e32 v196, 16, v69
	v_and_b32_e32 v197, 0xffff0000, v69
	v_mul_f32_e32 v42, v42, v196
	v_mul_f32_e32 v43, v43, v197
	v_cvt_pk_bf16_f32 v40, v40, v41
	v_cvt_pk_bf16_f32 v41, v42, v43
	v_mul_f32_e32 v44, v44, v2
	v_mul_f32_e32 v45, v45, v2
	v_mul_f32_e32 v46, v46, v2
	v_mul_f32_e32 v47, v47, v2
	v_lshlrev_b32_e32 v196, 16, v70
	v_and_b32_e32 v197, 0xffff0000, v70
	v_mul_f32_e32 v44, v44, v196
	v_mul_f32_e32 v45, v45, v197
	v_lshlrev_b32_e32 v196, 16, v71
	v_and_b32_e32 v197, 0xffff0000, v71
	v_mul_f32_e32 v46, v46, v196
	v_mul_f32_e32 v47, v47, v197
	v_cvt_pk_bf16_f32 v42, v44, v45
	v_cvt_pk_bf16_f32 v43, v46, v47
	s_nop 0
	v_permlane32_swap_b32_e32 v40, v42
	v_permlane32_swap_b32_e32 v41, v43
	global_store_dwordx4 v[8:9], v[40:43], off offset:32
	v_mul_f32_e32 v16, v16, v2
	v_mul_f32_e32 v17, v17, v2
	v_mul_f32_e32 v18, v18, v2
	v_mul_f32_e32 v19, v19, v2
	v_lshlrev_b32_e32 v196, 16, v72
	v_and_b32_e32 v197, 0xffff0000, v72
	v_mul_f32_e32 v16, v16, v196
	v_mul_f32_e32 v17, v17, v197
	v_lshlrev_b32_e32 v196, 16, v73
	v_and_b32_e32 v197, 0xffff0000, v73
	v_mul_f32_e32 v18, v18, v196
	v_mul_f32_e32 v19, v19, v197
	v_cvt_pk_bf16_f32 v16, v16, v17
	v_cvt_pk_bf16_f32 v17, v18, v19
	v_mul_f32_e32 v20, v20, v2
	v_mul_f32_e32 v21, v21, v2
	v_mul_f32_e32 v22, v22, v2
	v_mul_f32_e32 v23, v23, v2
	v_lshlrev_b32_e32 v196, 16, v74
	v_and_b32_e32 v197, 0xffff0000, v74
	v_mul_f32_e32 v20, v20, v196
	v_mul_f32_e32 v21, v21, v197
	v_lshlrev_b32_e32 v196, 16, v75
	v_and_b32_e32 v197, 0xffff0000, v75
	v_mul_f32_e32 v22, v22, v196
	v_mul_f32_e32 v23, v23, v197
	v_cvt_pk_bf16_f32 v18, v20, v21
	v_cvt_pk_bf16_f32 v19, v22, v23
	s_nop 0
	v_permlane32_swap_b32_e32 v16, v18
	v_permlane32_swap_b32_e32 v17, v19
	global_store_dwordx4 v[8:9], v[16:19], off offset:64
	v_mul_f32_e32 v24, v24, v2
	v_mul_f32_e32 v25, v25, v2
	v_mul_f32_e32 v26, v26, v2
	v_mul_f32_e32 v27, v27, v2
	v_lshlrev_b32_e32 v196, 16, v76
	v_and_b32_e32 v197, 0xffff0000, v76
	v_mul_f32_e32 v24, v24, v196
	v_mul_f32_e32 v25, v25, v197
	v_lshlrev_b32_e32 v196, 16, v77
	v_and_b32_e32 v197, 0xffff0000, v77
	v_mul_f32_e32 v26, v26, v196
	v_mul_f32_e32 v27, v27, v197
	v_cvt_pk_bf16_f32 v24, v24, v25
	v_cvt_pk_bf16_f32 v25, v26, v27
	v_mul_f32_e32 v28, v28, v2
	v_mul_f32_e32 v29, v29, v2
	v_mul_f32_e32 v30, v30, v2
	v_mul_f32_e32 v31, v31, v2
	v_lshlrev_b32_e32 v196, 16, v78
	v_and_b32_e32 v197, 0xffff0000, v78
	v_mul_f32_e32 v28, v28, v196
	v_mul_f32_e32 v29, v29, v197
	v_lshlrev_b32_e32 v196, 16, v79
	v_and_b32_e32 v197, 0xffff0000, v79
	v_mul_f32_e32 v30, v30, v196
	v_mul_f32_e32 v31, v31, v197
	v_cvt_pk_bf16_f32 v26, v28, v29
	v_cvt_pk_bf16_f32 v27, v30, v31
	s_nop 0
	v_permlane32_swap_b32_e32 v24, v26
	v_permlane32_swap_b32_e32 v25, v27
	global_store_dwordx4 v[8:9], v[24:27], off offset:96
	s_branch .LBB0_321
